# K|V|Q epilogue hand-regenerated: in-place rotary (no register copies), single V-tile test, 32-bit store offsets with scalar base, table reads a row group ahead
# speedup vs baseline: 1.0021x; 1.0021x over previous
.LBB0_307:
	ds_read_b32 v204, v156 offset:1024
	ds_read_b32 v208, v156 offset:0
	s_ashr_i32 s30, s26, 2
	s_lshl_b32 s9, s26, 2
	s_and_b32 s9, s9, 12
	s_or_b32 s19, s9, s51
	s_ashr_i32 s31, s30, 31
	s_lshl_b64 s[28:29], s[30:31], 25
	s_add_u32 s100, s49, s28
	s_addc_u32 s101, s50, s29
	v_lshl_add_u32 v194, s8, 8, v1
	v_lshl_or_b32 v195, s19, 7, v146
	v_lshl_add_u32 v194, v194, 11, v195
	s_cmp_eq_u32 s30, 1
	ds_read_b32 v206, v156 offset:1088
	ds_read_b32 v209, v156 offset:64
	s_waitcnt lgkmcnt(2)
	v_pk_mul_f32 v[126:127], v[126:127], v[204:205] op_sel_hi:[1,0]
	v_pk_mul_f32 v[128:129], v[128:129], v[204:205] op_sel_hi:[1,0]
	v_pk_mul_f32 v[122:123], v[122:123], v[204:205] op_sel_hi:[1,0]
	v_pk_mul_f32 v[124:125], v[124:125], v[204:205] op_sel_hi:[1,0]
	v_pk_mul_f32 v[118:119], v[118:119], v[204:205] op_sel_hi:[1,0]
	v_pk_mul_f32 v[120:121], v[120:121], v[204:205] op_sel_hi:[1,0]
	v_pk_mul_f32 v[114:115], v[114:115], v[204:205] op_sel_hi:[1,0]
	v_pk_mul_f32 v[116:117], v[116:117], v[204:205] op_sel_hi:[1,0]
	s_cbranch_scc1 .Lkq_norot0
	v_mul_f32_e32 v196, v148, v208
	v_mul_f32_e32 v197, v149, v208
	v_mul_f32_e32 v198, v150, v208
	v_mul_f32_e32 v199, v151, v208
	v_mul_f32_e32 v200, v152, v208
	v_mul_f32_e32 v201, v153, v208
	v_mul_f32_e32 v202, v154, v208
	v_mul_f32_e32 v203, v155, v208
	v_fract_f32_e32 v196, v196
	v_fract_f32_e32 v197, v197
	v_fract_f32_e32 v198, v198
	v_fract_f32_e32 v199, v199
	v_fract_f32_e32 v200, v200
	v_fract_f32_e32 v201, v201
	v_fract_f32_e32 v202, v202
	v_fract_f32_e32 v203, v203
	v_cos_f32_e32 v162, v196
	v_sin_f32_e32 v164, v196
	v_cos_f32_e32 v163, v197
	v_sin_f32_e32 v165, v197
	v_cos_f32_e32 v170, v198
	v_sin_f32_e32 v172, v198
	v_cos_f32_e32 v171, v199
	v_sin_f32_e32 v173, v199
	v_cos_f32_e32 v166, v200
	v_sin_f32_e32 v168, v200
	v_cos_f32_e32 v167, v201
	v_sin_f32_e32 v169, v201
	v_cos_f32_e32 v174, v202
	v_sin_f32_e32 v176, v202
	v_cos_f32_e32 v175, v203
	v_sin_f32_e32 v177, v203
	v_pk_mul_f32 v[178:179], v[118:119], v[164:165]
	v_pk_mul_f32 v[180:181], v[120:121], v[172:173]
	v_pk_mul_f32 v[182:183], v[114:115], v[168:169]
	v_pk_mul_f32 v[184:185], v[116:117], v[176:177]
	v_pk_mul_f32 v[186:187], v[126:127], v[164:165]
	v_pk_mul_f32 v[188:189], v[128:129], v[172:173]
	v_pk_mul_f32 v[190:191], v[122:123], v[168:169]
	v_pk_mul_f32 v[192:193], v[124:125], v[176:177]
	v_pk_fma_f32 v[126:127], v[126:127], v[162:163], v[178:179] neg_lo:[0,0,1] neg_hi:[0,0,1]
	v_pk_fma_f32 v[128:129], v[128:129], v[170:171], v[180:181] neg_lo:[0,0,1] neg_hi:[0,0,1]
	v_pk_fma_f32 v[122:123], v[122:123], v[166:167], v[182:183] neg_lo:[0,0,1] neg_hi:[0,0,1]
	v_pk_fma_f32 v[124:125], v[124:125], v[174:175], v[184:185] neg_lo:[0,0,1] neg_hi:[0,0,1]
	v_pk_fma_f32 v[118:119], v[118:119], v[162:163], v[186:187]
	v_pk_fma_f32 v[120:121], v[120:121], v[170:171], v[188:189]
	v_pk_fma_f32 v[114:115], v[114:115], v[166:167], v[190:191]
	v_pk_fma_f32 v[116:117], v[116:117], v[174:175], v[192:193]
.Lkq_norot0:
	v_cvt_pk_bf16_f32 v126, v126, v127
	v_cvt_pk_bf16_f32 v127, v128, v129
	v_cvt_pk_bf16_f32 v128, v122, v123
	v_cvt_pk_bf16_f32 v129, v124, v125
	v_cvt_pk_bf16_f32 v118, v118, v119
	v_cvt_pk_bf16_f32 v119, v120, v121
	v_cvt_pk_bf16_f32 v120, v114, v115
	v_cvt_pk_bf16_f32 v121, v116, v117
	global_store_dwordx4 v194, v[126:129], s[100:101] sc1
	s_nop 1
	global_store_dwordx4 v194, v[118:121], s[100:101] offset:64 sc1
	s_nop 1
	ds_read_b32 v204, v156 offset:1152
	ds_read_b32 v208, v156 offset:128
	s_waitcnt lgkmcnt(2)
	v_pk_mul_f32 v[110:111], v[110:111], v[206:207] op_sel_hi:[1,0]
	v_pk_mul_f32 v[112:113], v[112:113], v[206:207] op_sel_hi:[1,0]
	v_pk_mul_f32 v[106:107], v[106:107], v[206:207] op_sel_hi:[1,0]
	v_pk_mul_f32 v[108:109], v[108:109], v[206:207] op_sel_hi:[1,0]
	v_pk_mul_f32 v[102:103], v[102:103], v[206:207] op_sel_hi:[1,0]
	v_pk_mul_f32 v[104:105], v[104:105], v[206:207] op_sel_hi:[1,0]
	v_pk_mul_f32 v[98:99], v[98:99], v[206:207] op_sel_hi:[1,0]
	v_pk_mul_f32 v[100:101], v[100:101], v[206:207] op_sel_hi:[1,0]
	s_cbranch_scc1 .Lkq_norot1
	v_mul_f32_e32 v196, v148, v209
	v_mul_f32_e32 v197, v149, v209
	v_mul_f32_e32 v198, v150, v209
	v_mul_f32_e32 v199, v151, v209
	v_mul_f32_e32 v200, v152, v209
	v_mul_f32_e32 v201, v153, v209
	v_mul_f32_e32 v202, v154, v209
	v_mul_f32_e32 v203, v155, v209
	v_fract_f32_e32 v196, v196
	v_fract_f32_e32 v197, v197
	v_fract_f32_e32 v198, v198
	v_fract_f32_e32 v199, v199
	v_fract_f32_e32 v200, v200
	v_fract_f32_e32 v201, v201
	v_fract_f32_e32 v202, v202
	v_fract_f32_e32 v203, v203
	v_cos_f32_e32 v162, v196
	v_sin_f32_e32 v164, v196
	v_cos_f32_e32 v163, v197
	v_sin_f32_e32 v165, v197
	v_cos_f32_e32 v170, v198
	v_sin_f32_e32 v172, v198
	v_cos_f32_e32 v171, v199
	v_sin_f32_e32 v173, v199
	v_cos_f32_e32 v166, v200
	v_sin_f32_e32 v168, v200
	v_cos_f32_e32 v167, v201
	v_sin_f32_e32 v169, v201
	v_cos_f32_e32 v174, v202
	v_sin_f32_e32 v176, v202
	v_cos_f32_e32 v175, v203
	v_sin_f32_e32 v177, v203
	v_pk_mul_f32 v[178:179], v[102:103], v[164:165]
	v_pk_mul_f32 v[180:181], v[104:105], v[172:173]
	v_pk_mul_f32 v[182:183], v[98:99], v[168:169]
	v_pk_mul_f32 v[184:185], v[100:101], v[176:177]
	v_pk_mul_f32 v[186:187], v[110:111], v[164:165]
	v_pk_mul_f32 v[188:189], v[112:113], v[172:173]
	v_pk_mul_f32 v[190:191], v[106:107], v[168:169]
	v_pk_mul_f32 v[192:193], v[108:109], v[176:177]
	v_pk_fma_f32 v[110:111], v[110:111], v[162:163], v[178:179] neg_lo:[0,0,1] neg_hi:[0,0,1]
	v_pk_fma_f32 v[112:113], v[112:113], v[170:171], v[180:181] neg_lo:[0,0,1] neg_hi:[0,0,1]
	v_pk_fma_f32 v[106:107], v[106:107], v[166:167], v[182:183] neg_lo:[0,0,1] neg_hi:[0,0,1]
	v_pk_fma_f32 v[108:109], v[108:109], v[174:175], v[184:185] neg_lo:[0,0,1] neg_hi:[0,0,1]
	v_pk_fma_f32 v[102:103], v[102:103], v[162:163], v[186:187]
	v_pk_fma_f32 v[104:105], v[104:105], v[170:171], v[188:189]
	v_pk_fma_f32 v[98:99], v[98:99], v[166:167], v[190:191]
	v_pk_fma_f32 v[100:101], v[100:101], v[174:175], v[192:193]
.Lkq_norot1:
	v_cvt_pk_bf16_f32 v110, v110, v111
	v_cvt_pk_bf16_f32 v111, v112, v113
	v_cvt_pk_bf16_f32 v112, v106, v107
	v_cvt_pk_bf16_f32 v113, v108, v109
	v_cvt_pk_bf16_f32 v102, v102, v103
	v_cvt_pk_bf16_f32 v103, v104, v105
	v_cvt_pk_bf16_f32 v104, v98, v99
	v_cvt_pk_bf16_f32 v105, v100, v101
	v_add_u32_e32 v195, 0x8000, v194
	global_store_dwordx4 v195, v[110:113], s[100:101] sc1
	s_nop 1
	global_store_dwordx4 v195, v[102:105], s[100:101] offset:64 sc1
	s_nop 1
	ds_read_b32 v206, v156 offset:1216
	ds_read_b32 v209, v156 offset:192
	s_waitcnt lgkmcnt(2)
	v_pk_mul_f32 v[94:95], v[94:95], v[204:205] op_sel_hi:[1,0]
	v_pk_mul_f32 v[96:97], v[96:97], v[204:205] op_sel_hi:[1,0]
	v_pk_mul_f32 v[90:91], v[90:91], v[204:205] op_sel_hi:[1,0]
	v_pk_mul_f32 v[92:93], v[92:93], v[204:205] op_sel_hi:[1,0]
	v_pk_mul_f32 v[86:87], v[86:87], v[204:205] op_sel_hi:[1,0]
	v_pk_mul_f32 v[88:89], v[88:89], v[204:205] op_sel_hi:[1,0]
	v_pk_mul_f32 v[82:83], v[82:83], v[204:205] op_sel_hi:[1,0]
	v_pk_mul_f32 v[84:85], v[84:85], v[204:205] op_sel_hi:[1,0]
	s_cbranch_scc1 .Lkq_norot2
	v_mul_f32_e32 v196, v148, v208
	v_mul_f32_e32 v197, v149, v208
	v_mul_f32_e32 v198, v150, v208
	v_mul_f32_e32 v199, v151, v208
	v_mul_f32_e32 v200, v152, v208
	v_mul_f32_e32 v201, v153, v208
	v_mul_f32_e32 v202, v154, v208
	v_mul_f32_e32 v203, v155, v208
	v_fract_f32_e32 v196, v196
	v_fract_f32_e32 v197, v197
	v_fract_f32_e32 v198, v198
	v_fract_f32_e32 v199, v199
	v_fract_f32_e32 v200, v200
	v_fract_f32_e32 v201, v201
	v_fract_f32_e32 v202, v202
	v_fract_f32_e32 v203, v203
	v_cos_f32_e32 v162, v196
	v_sin_f32_e32 v164, v196
	v_cos_f32_e32 v163, v197
	v_sin_f32_e32 v165, v197
	v_cos_f32_e32 v170, v198
	v_sin_f32_e32 v172, v198
	v_cos_f32_e32 v171, v199
	v_sin_f32_e32 v173, v199
	v_cos_f32_e32 v166, v200
	v_sin_f32_e32 v168, v200
	v_cos_f32_e32 v167, v201
	v_sin_f32_e32 v169, v201
	v_cos_f32_e32 v174, v202
	v_sin_f32_e32 v176, v202
	v_cos_f32_e32 v175, v203
	v_sin_f32_e32 v177, v203
	v_pk_mul_f32 v[178:179], v[86:87], v[164:165]
	v_pk_mul_f32 v[180:181], v[88:89], v[172:173]
	v_pk_mul_f32 v[182:183], v[82:83], v[168:169]
	v_pk_mul_f32 v[184:185], v[84:85], v[176:177]
	v_pk_mul_f32 v[186:187], v[94:95], v[164:165]
	v_pk_mul_f32 v[188:189], v[96:97], v[172:173]
	v_pk_mul_f32 v[190:191], v[90:91], v[168:169]
	v_pk_mul_f32 v[192:193], v[92:93], v[176:177]
	v_pk_fma_f32 v[94:95], v[94:95], v[162:163], v[178:179] neg_lo:[0,0,1] neg_hi:[0,0,1]
	v_pk_fma_f32 v[96:97], v[96:97], v[170:171], v[180:181] neg_lo:[0,0,1] neg_hi:[0,0,1]
	v_pk_fma_f32 v[90:91], v[90:91], v[166:167], v[182:183] neg_lo:[0,0,1] neg_hi:[0,0,1]
	v_pk_fma_f32 v[92:93], v[92:93], v[174:175], v[184:185] neg_lo:[0,0,1] neg_hi:[0,0,1]
	v_pk_fma_f32 v[86:87], v[86:87], v[162:163], v[186:187]
	v_pk_fma_f32 v[88:89], v[88:89], v[170:171], v[188:189]
	v_pk_fma_f32 v[82:83], v[82:83], v[166:167], v[190:191]
	v_pk_fma_f32 v[84:85], v[84:85], v[174:175], v[192:193]
.Lkq_norot2:
	v_cvt_pk_bf16_f32 v94, v94, v95
	v_cvt_pk_bf16_f32 v95, v96, v97
	v_cvt_pk_bf16_f32 v96, v90, v91
	v_cvt_pk_bf16_f32 v97, v92, v93
	v_cvt_pk_bf16_f32 v86, v86, v87
	v_cvt_pk_bf16_f32 v87, v88, v89
	v_cvt_pk_bf16_f32 v88, v82, v83
	v_cvt_pk_bf16_f32 v89, v84, v85
	v_add_u32_e32 v207, 0x10000, v194
	global_store_dwordx4 v207, v[94:97], s[100:101] sc1
	s_nop 1
	global_store_dwordx4 v207, v[86:89], s[100:101] offset:64 sc1
	s_nop 1
	ds_read_b32 v204, v156 offset:1536
	ds_read_b32 v208, v156 offset:512
	s_waitcnt lgkmcnt(2)
	v_pk_mul_f32 v[78:79], v[78:79], v[206:207] op_sel_hi:[1,0]
	v_pk_mul_f32 v[80:81], v[80:81], v[206:207] op_sel_hi:[1,0]
	v_pk_mul_f32 v[74:75], v[74:75], v[206:207] op_sel_hi:[1,0]
	v_pk_mul_f32 v[76:77], v[76:77], v[206:207] op_sel_hi:[1,0]
	v_pk_mul_f32 v[70:71], v[70:71], v[206:207] op_sel_hi:[1,0]
	v_pk_mul_f32 v[72:73], v[72:73], v[206:207] op_sel_hi:[1,0]
	v_pk_mul_f32 v[66:67], v[66:67], v[206:207] op_sel_hi:[1,0]
	v_pk_mul_f32 v[68:69], v[68:69], v[206:207] op_sel_hi:[1,0]
	s_cbranch_scc1 .Lkq_norot3
	v_mul_f32_e32 v196, v148, v209
	v_mul_f32_e32 v197, v149, v209
	v_mul_f32_e32 v198, v150, v209
	v_mul_f32_e32 v199, v151, v209
	v_mul_f32_e32 v200, v152, v209
	v_mul_f32_e32 v201, v153, v209
	v_mul_f32_e32 v202, v154, v209
	v_mul_f32_e32 v203, v155, v209
	v_fract_f32_e32 v196, v196
	v_fract_f32_e32 v197, v197
	v_fract_f32_e32 v198, v198
	v_fract_f32_e32 v199, v199
	v_fract_f32_e32 v200, v200
	v_fract_f32_e32 v201, v201
	v_fract_f32_e32 v202, v202
	v_fract_f32_e32 v203, v203
	v_cos_f32_e32 v162, v196
	v_sin_f32_e32 v164, v196
	v_cos_f32_e32 v163, v197
	v_sin_f32_e32 v165, v197
	v_cos_f32_e32 v170, v198
	v_sin_f32_e32 v172, v198
	v_cos_f32_e32 v171, v199
	v_sin_f32_e32 v173, v199
	v_cos_f32_e32 v166, v200
	v_sin_f32_e32 v168, v200
	v_cos_f32_e32 v167, v201
	v_sin_f32_e32 v169, v201
	v_cos_f32_e32 v174, v202
	v_sin_f32_e32 v176, v202
	v_cos_f32_e32 v175, v203
	v_sin_f32_e32 v177, v203
	v_pk_mul_f32 v[178:179], v[70:71], v[164:165]
	v_pk_mul_f32 v[180:181], v[72:73], v[172:173]
	v_pk_mul_f32 v[182:183], v[66:67], v[168:169]
	v_pk_mul_f32 v[184:185], v[68:69], v[176:177]
	v_pk_mul_f32 v[186:187], v[78:79], v[164:165]
	v_pk_mul_f32 v[188:189], v[80:81], v[172:173]
	v_pk_mul_f32 v[190:191], v[74:75], v[168:169]
	v_pk_mul_f32 v[192:193], v[76:77], v[176:177]
	v_pk_fma_f32 v[78:79], v[78:79], v[162:163], v[178:179] neg_lo:[0,0,1] neg_hi:[0,0,1]
	v_pk_fma_f32 v[80:81], v[80:81], v[170:171], v[180:181] neg_lo:[0,0,1] neg_hi:[0,0,1]
	v_pk_fma_f32 v[74:75], v[74:75], v[166:167], v[182:183] neg_lo:[0,0,1] neg_hi:[0,0,1]
	v_pk_fma_f32 v[76:77], v[76:77], v[174:175], v[184:185] neg_lo:[0,0,1] neg_hi:[0,0,1]
	v_pk_fma_f32 v[70:71], v[70:71], v[162:163], v[186:187]
	v_pk_fma_f32 v[72:73], v[72:73], v[170:171], v[188:189]
	v_pk_fma_f32 v[66:67], v[66:67], v[166:167], v[190:191]
	v_pk_fma_f32 v[68:69], v[68:69], v[174:175], v[192:193]
.Lkq_norot3:
	v_cvt_pk_bf16_f32 v78, v78, v79
	v_cvt_pk_bf16_f32 v79, v80, v81
	v_cvt_pk_bf16_f32 v80, v74, v75
	v_cvt_pk_bf16_f32 v81, v76, v77
	v_cvt_pk_bf16_f32 v70, v70, v71
	v_cvt_pk_bf16_f32 v71, v72, v73
	v_cvt_pk_bf16_f32 v72, v66, v67
	v_cvt_pk_bf16_f32 v73, v68, v69
	v_add_u32_e32 v195, 0x18000, v194
	global_store_dwordx4 v195, v[78:81], s[100:101] sc1
	s_nop 1
	global_store_dwordx4 v195, v[70:73], s[100:101] offset:64 sc1
	s_nop 1
	ds_read_b32 v206, v156 offset:1600
	ds_read_b32 v209, v156 offset:576
	s_waitcnt lgkmcnt(2)
	v_pk_mul_f32 v[62:63], v[62:63], v[204:205] op_sel_hi:[1,0]
	v_pk_mul_f32 v[64:65], v[64:65], v[204:205] op_sel_hi:[1,0]
	v_pk_mul_f32 v[58:59], v[58:59], v[204:205] op_sel_hi:[1,0]
	v_pk_mul_f32 v[60:61], v[60:61], v[204:205] op_sel_hi:[1,0]
	v_pk_mul_f32 v[54:55], v[54:55], v[204:205] op_sel_hi:[1,0]
	v_pk_mul_f32 v[56:57], v[56:57], v[204:205] op_sel_hi:[1,0]
	v_pk_mul_f32 v[50:51], v[50:51], v[204:205] op_sel_hi:[1,0]
	v_pk_mul_f32 v[52:53], v[52:53], v[204:205] op_sel_hi:[1,0]
	s_cbranch_scc1 .Lkq_norot4
	v_mul_f32_e32 v196, v148, v208
	v_mul_f32_e32 v197, v149, v208
	v_mul_f32_e32 v198, v150, v208
	v_mul_f32_e32 v199, v151, v208
	v_mul_f32_e32 v200, v152, v208
	v_mul_f32_e32 v201, v153, v208
	v_mul_f32_e32 v202, v154, v208
	v_mul_f32_e32 v203, v155, v208
	v_fract_f32_e32 v196, v196
	v_fract_f32_e32 v197, v197
	v_fract_f32_e32 v198, v198
	v_fract_f32_e32 v199, v199
	v_fract_f32_e32 v200, v200
	v_fract_f32_e32 v201, v201
	v_fract_f32_e32 v202, v202
	v_fract_f32_e32 v203, v203
	v_cos_f32_e32 v162, v196
	v_sin_f32_e32 v164, v196
	v_cos_f32_e32 v163, v197
	v_sin_f32_e32 v165, v197
	v_cos_f32_e32 v170, v198
	v_sin_f32_e32 v172, v198
	v_cos_f32_e32 v171, v199
	v_sin_f32_e32 v173, v199
	v_cos_f32_e32 v166, v200
	v_sin_f32_e32 v168, v200
	v_cos_f32_e32 v167, v201
	v_sin_f32_e32 v169, v201
	v_cos_f32_e32 v174, v202
	v_sin_f32_e32 v176, v202
	v_cos_f32_e32 v175, v203
	v_sin_f32_e32 v177, v203
	v_pk_mul_f32 v[178:179], v[54:55], v[164:165]
	v_pk_mul_f32 v[180:181], v[56:57], v[172:173]
	v_pk_mul_f32 v[182:183], v[50:51], v[168:169]
	v_pk_mul_f32 v[184:185], v[52:53], v[176:177]
	v_pk_mul_f32 v[186:187], v[62:63], v[164:165]
	v_pk_mul_f32 v[188:189], v[64:65], v[172:173]
	v_pk_mul_f32 v[190:191], v[58:59], v[168:169]
	v_pk_mul_f32 v[192:193], v[60:61], v[176:177]
	v_pk_fma_f32 v[62:63], v[62:63], v[162:163], v[178:179] neg_lo:[0,0,1] neg_hi:[0,0,1]
	v_pk_fma_f32 v[64:65], v[64:65], v[170:171], v[180:181] neg_lo:[0,0,1] neg_hi:[0,0,1]
	v_pk_fma_f32 v[58:59], v[58:59], v[166:167], v[182:183] neg_lo:[0,0,1] neg_hi:[0,0,1]
	v_pk_fma_f32 v[60:61], v[60:61], v[174:175], v[184:185] neg_lo:[0,0,1] neg_hi:[0,0,1]
	v_pk_fma_f32 v[54:55], v[54:55], v[162:163], v[186:187]
	v_pk_fma_f32 v[56:57], v[56:57], v[170:171], v[188:189]
	v_pk_fma_f32 v[50:51], v[50:51], v[166:167], v[190:191]
	v_pk_fma_f32 v[52:53], v[52:53], v[174:175], v[192:193]
.Lkq_norot4:
	v_cvt_pk_bf16_f32 v62, v62, v63
	v_cvt_pk_bf16_f32 v63, v64, v65
	v_cvt_pk_bf16_f32 v64, v58, v59
	v_cvt_pk_bf16_f32 v65, v60, v61
	v_cvt_pk_bf16_f32 v54, v54, v55
	v_cvt_pk_bf16_f32 v55, v56, v57
	v_cvt_pk_bf16_f32 v56, v50, v51
	v_cvt_pk_bf16_f32 v57, v52, v53
	v_add_u32_e32 v207, 0x40000, v194
	global_store_dwordx4 v207, v[62:65], s[100:101] sc1
	s_nop 1
	global_store_dwordx4 v207, v[54:57], s[100:101] offset:64 sc1
	s_nop 1
	ds_read_b32 v204, v156 offset:1664
	ds_read_b32 v208, v156 offset:640
	s_waitcnt lgkmcnt(2)
	v_pk_mul_f32 v[46:47], v[46:47], v[206:207] op_sel_hi:[1,0]
	v_pk_mul_f32 v[48:49], v[48:49], v[206:207] op_sel_hi:[1,0]
	v_pk_mul_f32 v[42:43], v[42:43], v[206:207] op_sel_hi:[1,0]
	v_pk_mul_f32 v[44:45], v[44:45], v[206:207] op_sel_hi:[1,0]
	v_pk_mul_f32 v[38:39], v[38:39], v[206:207] op_sel_hi:[1,0]
	v_pk_mul_f32 v[40:41], v[40:41], v[206:207] op_sel_hi:[1,0]
	v_pk_mul_f32 v[34:35], v[34:35], v[206:207] op_sel_hi:[1,0]
	v_pk_mul_f32 v[36:37], v[36:37], v[206:207] op_sel_hi:[1,0]
	s_cbranch_scc1 .Lkq_norot5
	v_mul_f32_e32 v196, v148, v209
	v_mul_f32_e32 v197, v149, v209
	v_mul_f32_e32 v198, v150, v209
	v_mul_f32_e32 v199, v151, v209
	v_mul_f32_e32 v200, v152, v209
	v_mul_f32_e32 v201, v153, v209
	v_mul_f32_e32 v202, v154, v209
	v_mul_f32_e32 v203, v155, v209
	v_fract_f32_e32 v196, v196
	v_fract_f32_e32 v197, v197
	v_fract_f32_e32 v198, v198
	v_fract_f32_e32 v199, v199
	v_fract_f32_e32 v200, v200
	v_fract_f32_e32 v201, v201
	v_fract_f32_e32 v202, v202
	v_fract_f32_e32 v203, v203
	v_cos_f32_e32 v162, v196
	v_sin_f32_e32 v164, v196
	v_cos_f32_e32 v163, v197
	v_sin_f32_e32 v165, v197
	v_cos_f32_e32 v170, v198
	v_sin_f32_e32 v172, v198
	v_cos_f32_e32 v171, v199
	v_sin_f32_e32 v173, v199
	v_cos_f32_e32 v166, v200
	v_sin_f32_e32 v168, v200
	v_cos_f32_e32 v167, v201
	v_sin_f32_e32 v169, v201
	v_cos_f32_e32 v174, v202
	v_sin_f32_e32 v176, v202
	v_cos_f32_e32 v175, v203
	v_sin_f32_e32 v177, v203
	v_pk_mul_f32 v[178:179], v[38:39], v[164:165]
	v_pk_mul_f32 v[180:181], v[40:41], v[172:173]
	v_pk_mul_f32 v[182:183], v[34:35], v[168:169]
	v_pk_mul_f32 v[184:185], v[36:37], v[176:177]
	v_pk_mul_f32 v[186:187], v[46:47], v[164:165]
	v_pk_mul_f32 v[188:189], v[48:49], v[172:173]
	v_pk_mul_f32 v[190:191], v[42:43], v[168:169]
	v_pk_mul_f32 v[192:193], v[44:45], v[176:177]
	v_pk_fma_f32 v[46:47], v[46:47], v[162:163], v[178:179] neg_lo:[0,0,1] neg_hi:[0,0,1]
	v_pk_fma_f32 v[48:49], v[48:49], v[170:171], v[180:181] neg_lo:[0,0,1] neg_hi:[0,0,1]
	v_pk_fma_f32 v[42:43], v[42:43], v[166:167], v[182:183] neg_lo:[0,0,1] neg_hi:[0,0,1]
	v_pk_fma_f32 v[44:45], v[44:45], v[174:175], v[184:185] neg_lo:[0,0,1] neg_hi:[0,0,1]
	v_pk_fma_f32 v[38:39], v[38:39], v[162:163], v[186:187]
	v_pk_fma_f32 v[40:41], v[40:41], v[170:171], v[188:189]
	v_pk_fma_f32 v[34:35], v[34:35], v[166:167], v[190:191]
	v_pk_fma_f32 v[36:37], v[36:37], v[174:175], v[192:193]
.Lkq_norot5:
	v_cvt_pk_bf16_f32 v46, v46, v47
	v_cvt_pk_bf16_f32 v47, v48, v49
	v_cvt_pk_bf16_f32 v48, v42, v43
	v_cvt_pk_bf16_f32 v49, v44, v45
	v_cvt_pk_bf16_f32 v38, v38, v39
	v_cvt_pk_bf16_f32 v39, v40, v41
	v_cvt_pk_bf16_f32 v40, v34, v35
	v_cvt_pk_bf16_f32 v41, v36, v37
	v_add_u32_e32 v195, 0x48000, v194
	global_store_dwordx4 v195, v[46:49], s[100:101] sc1
	s_nop 1
	global_store_dwordx4 v195, v[38:41], s[100:101] offset:64 sc1
	s_nop 1
	ds_read_b32 v206, v156 offset:1728
	ds_read_b32 v209, v156 offset:704
	s_waitcnt lgkmcnt(2)
	v_pk_mul_f32 v[30:31], v[30:31], v[204:205] op_sel_hi:[1,0]
	v_pk_mul_f32 v[32:33], v[32:33], v[204:205] op_sel_hi:[1,0]
	v_pk_mul_f32 v[26:27], v[26:27], v[204:205] op_sel_hi:[1,0]
	v_pk_mul_f32 v[28:29], v[28:29], v[204:205] op_sel_hi:[1,0]
	v_pk_mul_f32 v[22:23], v[22:23], v[204:205] op_sel_hi:[1,0]
	v_pk_mul_f32 v[24:25], v[24:25], v[204:205] op_sel_hi:[1,0]
	v_pk_mul_f32 v[18:19], v[18:19], v[204:205] op_sel_hi:[1,0]
	v_pk_mul_f32 v[20:21], v[20:21], v[204:205] op_sel_hi:[1,0]
	s_cbranch_scc1 .Lkq_norot6
	v_mul_f32_e32 v196, v148, v208
	v_mul_f32_e32 v197, v149, v208
	v_mul_f32_e32 v198, v150, v208
	v_mul_f32_e32 v199, v151, v208
	v_mul_f32_e32 v200, v152, v208
	v_mul_f32_e32 v201, v153, v208
	v_mul_f32_e32 v202, v154, v208
	v_mul_f32_e32 v203, v155, v208
	v_fract_f32_e32 v196, v196
	v_fract_f32_e32 v197, v197
	v_fract_f32_e32 v198, v198
	v_fract_f32_e32 v199, v199
	v_fract_f32_e32 v200, v200
	v_fract_f32_e32 v201, v201
	v_fract_f32_e32 v202, v202
	v_fract_f32_e32 v203, v203
	v_cos_f32_e32 v162, v196
	v_sin_f32_e32 v164, v196
	v_cos_f32_e32 v163, v197
	v_sin_f32_e32 v165, v197
	v_cos_f32_e32 v170, v198
	v_sin_f32_e32 v172, v198
	v_cos_f32_e32 v171, v199
	v_sin_f32_e32 v173, v199
	v_cos_f32_e32 v166, v200
	v_sin_f32_e32 v168, v200
	v_cos_f32_e32 v167, v201
	v_sin_f32_e32 v169, v201
	v_cos_f32_e32 v174, v202
	v_sin_f32_e32 v176, v202
	v_cos_f32_e32 v175, v203
	v_sin_f32_e32 v177, v203
	v_pk_mul_f32 v[178:179], v[22:23], v[164:165]
	v_pk_mul_f32 v[180:181], v[24:25], v[172:173]
	v_pk_mul_f32 v[182:183], v[18:19], v[168:169]
	v_pk_mul_f32 v[184:185], v[20:21], v[176:177]
	v_pk_mul_f32 v[186:187], v[30:31], v[164:165]
	v_pk_mul_f32 v[188:189], v[32:33], v[172:173]
	v_pk_mul_f32 v[190:191], v[26:27], v[168:169]
	v_pk_mul_f32 v[192:193], v[28:29], v[176:177]
	v_pk_fma_f32 v[30:31], v[30:31], v[162:163], v[178:179] neg_lo:[0,0,1] neg_hi:[0,0,1]
	v_pk_fma_f32 v[32:33], v[32:33], v[170:171], v[180:181] neg_lo:[0,0,1] neg_hi:[0,0,1]
	v_pk_fma_f32 v[26:27], v[26:27], v[166:167], v[182:183] neg_lo:[0,0,1] neg_hi:[0,0,1]
	v_pk_fma_f32 v[28:29], v[28:29], v[174:175], v[184:185] neg_lo:[0,0,1] neg_hi:[0,0,1]
	v_pk_fma_f32 v[22:23], v[22:23], v[162:163], v[186:187]
	v_pk_fma_f32 v[24:25], v[24:25], v[170:171], v[188:189]
	v_pk_fma_f32 v[18:19], v[18:19], v[166:167], v[190:191]
	v_pk_fma_f32 v[20:21], v[20:21], v[174:175], v[192:193]
.Lkq_norot6:
	v_cvt_pk_bf16_f32 v30, v30, v31
	v_cvt_pk_bf16_f32 v31, v32, v33
	v_cvt_pk_bf16_f32 v32, v26, v27
	v_cvt_pk_bf16_f32 v33, v28, v29
	v_cvt_pk_bf16_f32 v22, v22, v23
	v_cvt_pk_bf16_f32 v23, v24, v25
	v_cvt_pk_bf16_f32 v24, v18, v19
	v_cvt_pk_bf16_f32 v25, v20, v21
	v_add_u32_e32 v207, 0x50000, v194
	global_store_dwordx4 v207, v[30:33], s[100:101] sc1
	s_nop 1
	global_store_dwordx4 v207, v[22:25], s[100:101] offset:64 sc1
	s_nop 1
	s_waitcnt lgkmcnt(0)
	v_pk_mul_f32 v[14:15], v[14:15], v[206:207] op_sel_hi:[1,0]
	v_pk_mul_f32 v[16:17], v[16:17], v[206:207] op_sel_hi:[1,0]
	v_pk_mul_f32 v[10:11], v[10:11], v[206:207] op_sel_hi:[1,0]
	v_pk_mul_f32 v[12:13], v[12:13], v[206:207] op_sel_hi:[1,0]
	v_pk_mul_f32 v[6:7], v[6:7], v[206:207] op_sel_hi:[1,0]
	v_pk_mul_f32 v[8:9], v[8:9], v[206:207] op_sel_hi:[1,0]
	v_pk_mul_f32 v[2:3], v[2:3], v[206:207] op_sel_hi:[1,0]
	v_pk_mul_f32 v[4:5], v[4:5], v[206:207] op_sel_hi:[1,0]
	s_cbranch_scc1 .Lkq_norot7
	v_mul_f32_e32 v196, v148, v209
	v_mul_f32_e32 v197, v149, v209
	v_mul_f32_e32 v198, v150, v209
	v_mul_f32_e32 v199, v151, v209
	v_mul_f32_e32 v200, v152, v209
	v_mul_f32_e32 v201, v153, v209
	v_mul_f32_e32 v202, v154, v209
	v_mul_f32_e32 v203, v155, v209
	v_fract_f32_e32 v196, v196
	v_fract_f32_e32 v197, v197
	v_fract_f32_e32 v198, v198
	v_fract_f32_e32 v199, v199
	v_fract_f32_e32 v200, v200
	v_fract_f32_e32 v201, v201
	v_fract_f32_e32 v202, v202
	v_fract_f32_e32 v203, v203
	v_cos_f32_e32 v162, v196
	v_sin_f32_e32 v164, v196
	v_cos_f32_e32 v163, v197
	v_sin_f32_e32 v165, v197
	v_cos_f32_e32 v170, v198
	v_sin_f32_e32 v172, v198
	v_cos_f32_e32 v171, v199
	v_sin_f32_e32 v173, v199
	v_cos_f32_e32 v166, v200
	v_sin_f32_e32 v168, v200
	v_cos_f32_e32 v167, v201
	v_sin_f32_e32 v169, v201
	v_cos_f32_e32 v174, v202
	v_sin_f32_e32 v176, v202
	v_cos_f32_e32 v175, v203
	v_sin_f32_e32 v177, v203
	v_pk_mul_f32 v[178:179], v[6:7], v[164:165]
	v_pk_mul_f32 v[180:181], v[8:9], v[172:173]
	v_pk_mul_f32 v[182:183], v[2:3], v[168:169]
	v_pk_mul_f32 v[184:185], v[4:5], v[176:177]
	v_pk_mul_f32 v[186:187], v[14:15], v[164:165]
	v_pk_mul_f32 v[188:189], v[16:17], v[172:173]
	v_pk_mul_f32 v[190:191], v[10:11], v[168:169]
	v_pk_mul_f32 v[192:193], v[12:13], v[176:177]
	v_pk_fma_f32 v[14:15], v[14:15], v[162:163], v[178:179] neg_lo:[0,0,1] neg_hi:[0,0,1]
	v_pk_fma_f32 v[16:17], v[16:17], v[170:171], v[180:181] neg_lo:[0,0,1] neg_hi:[0,0,1]
	v_pk_fma_f32 v[10:11], v[10:11], v[166:167], v[182:183] neg_lo:[0,0,1] neg_hi:[0,0,1]
	v_pk_fma_f32 v[12:13], v[12:13], v[174:175], v[184:185] neg_lo:[0,0,1] neg_hi:[0,0,1]
	v_pk_fma_f32 v[6:7], v[6:7], v[162:163], v[186:187]
	v_pk_fma_f32 v[8:9], v[8:9], v[170:171], v[188:189]
	v_pk_fma_f32 v[2:3], v[2:3], v[166:167], v[190:191]
	v_pk_fma_f32 v[4:5], v[4:5], v[174:175], v[192:193]
.Lkq_norot7:
	v_cvt_pk_bf16_f32 v14, v14, v15
	v_cvt_pk_bf16_f32 v15, v16, v17
	v_cvt_pk_bf16_f32 v16, v10, v11
	v_cvt_pk_bf16_f32 v17, v12, v13
	v_cvt_pk_bf16_f32 v6, v6, v7
	v_cvt_pk_bf16_f32 v7, v8, v9
	v_cvt_pk_bf16_f32 v8, v2, v3
	v_cvt_pk_bf16_f32 v9, v4, v5
	v_add_u32_e32 v195, 0x58000, v194
	global_store_dwordx4 v195, v[14:17], s[100:101] sc1
	s_nop 1
	global_store_dwordx4 v195, v[6:9], s[100:101] offset:64 sc1
	s_nop 1
	s_andn2_b64 vcc, exec, s[6:7]
	s_mov_b64 s[6:7], -1
	s_cbranch_vccnz .LBB0_284
	s_andn2_b64 vcc, exec, s[10:11]
	s_cbranch_vccnz .LBB0_283
	s_barrier
	s_branch .LBB0_283

.LBB0_362:
	s_ashr_i32 s23, s22, 31
	s_lshl_b64 s[24:25], s[22:23], 19
	s_add_u32 s24, s80, s24
	s_addc_u32 s25, s81, s25
	s_and_b64 s[26:27], s[6:7], exec
	s_cselect_b32 s23, s25, s35
	s_cselect_b32 s39, s24, s34
	s_ashr_i32 s21, s20, 31
	s_lshl_b64 s[26:27], s[20:21], 19
	s_add_u32 s26, s45, s26
	s_addc_u32 s27, s46, s27
	s_and_b64 s[36:37], s[6:7], exec
	s_cselect_b32 s21, s27, s31
	s_cselect_b32 s40, s26, s30
	s_add_u32 s41, s30, 0x100
	s_addc_u32 s43, s31, 0
	s_add_u32 s30, s34, 0x40080
	s_addc_u32 s31, s35, 0
	s_mov_b32 s56, -2
	s_add_u32 s34, s30, 0xfffc0080
	s_addc_u32 s35, s31, -1
	s_add_i32 s57, 0, 0x10000
	s_cmp_eq_u32 s56, 12
	s_cselect_b32 s37, s23, s35
	s_cselect_b32 s36, s39, s34
	v_add_u32_e32 v146, s57, v155
	s_cselect_b32 s35, s21, s43
	s_cselect_b32 s34, s40, s41
	s_add_i32 s60, 0, 0x14000
	ds_read_b128 v[142:145], v146
	ds_read_b128 v[168:171], v146 offset:1024
	ds_read_b128 v[172:175], v146 offset:2048
	ds_read_b128 v[176:179], v146 offset:3072
	v_add_u32_e32 v146, s60, v155
	ds_read_b128 v[180:183], v146
	ds_read_b128 v[184:187], v146 offset:1024
	ds_read_b128 v[188:191], v146 offset:2048
	ds_read_b128 v[192:195], v146 offset:3072
	v_lshl_add_u64 v[146:147], s[30:31], 0, v[140:141]
	s_add_i32 m0, s48, 0xc000
	ds_read_b128 v[196:199], v157
	ds_read_b128 v[200:203], v157 offset:1024
	ds_read_b128 v[204:207], v157 offset:2048
	ds_read_b128 v[220:223], v157 offset:3072
	ds_read_b128 v[236:239], v157 offset:4096
	ds_read_b128 v[240:243], v157 offset:5120
	ds_read_b128 v[244:247], v157 offset:6144
	ds_read_b128 v[248:251], v157 offset:7168
	global_load_lds_dwordx4 v[146:147], off
	v_lshl_add_u64 v[146:147], s[30:31], 0, v[138:139]
	s_add_i32 m0, s48, 0xe000
	s_nop 0
	global_load_lds_dwordx4 v[146:147], off
	s_nop 0
	s_nop 0
	s_nop 0
	s_nop 0
	s_nop 0
	s_nop 0
	s_nop 0
	s_nop 0
	s_nop 0
	s_nop 0
	s_nop 0
	s_nop 0
	s_nop 0
	s_nop 0
	s_nop 0
	s_nop 0
	s_nop 0
	s_nop 0
	s_nop 0
	s_nop 0
	s_nop 0
	s_nop 0
	s_waitcnt vmcnt(8)
	s_waitcnt lgkmcnt(0)
	s_barrier
	s_waitcnt lgkmcnt(0)
	v_mfma_f32_16x16x32_bf16 v[126:129], v[142:145], v[196:199], 0
	v_mfma_f32_16x16x32_bf16 v[118:121], v[172:175], v[196:199], 0
	v_mfma_f32_16x16x32_bf16 v[110:113], v[142:145], v[204:207], 0
	v_mfma_f32_16x16x32_bf16 v[102:105], v[172:175], v[204:207], 0
	v_mfma_f32_16x16x32_bf16 v[94:97], v[142:145], v[236:239], 0
	v_mfma_f32_16x16x32_bf16 v[86:89], v[172:175], v[236:239], 0
	v_mfma_f32_16x16x32_bf16 v[78:81], v[142:145], v[244:247], 0
	v_mfma_f32_16x16x32_bf16 v[70:73], v[172:175], v[244:247], 0
	v_mfma_f32_16x16x32_bf16 v[126:129], v[168:171], v[200:203], v[126:129]
	v_mfma_f32_16x16x32_bf16 v[118:121], v[176:179], v[200:203], v[118:121]
	v_mfma_f32_16x16x32_bf16 v[110:113], v[168:171], v[220:223], v[110:113]
	v_mfma_f32_16x16x32_bf16 v[102:105], v[176:179], v[220:223], v[102:105]
	v_mfma_f32_16x16x32_bf16 v[94:97], v[168:171], v[240:243], v[94:97]
	v_mfma_f32_16x16x32_bf16 v[86:89], v[176:179], v[240:243], v[86:89]
	v_mfma_f32_16x16x32_bf16 v[78:81], v[168:171], v[248:251], v[78:81]
	v_mfma_f32_16x16x32_bf16 v[70:73], v[176:179], v[248:251], v[70:73]
	v_mfma_f32_16x16x32_bf16 v[122:125], v[180:183], v[196:199], 0
	v_mfma_f32_16x16x32_bf16 v[114:117], v[188:191], v[196:199], 0
	v_mfma_f32_16x16x32_bf16 v[106:109], v[180:183], v[204:207], 0
	v_mfma_f32_16x16x32_bf16 v[98:101], v[188:191], v[204:207], 0
	v_mfma_f32_16x16x32_bf16 v[90:93], v[180:183], v[236:239], 0
	v_mfma_f32_16x16x32_bf16 v[82:85], v[188:191], v[236:239], 0
	v_mfma_f32_16x16x32_bf16 v[74:77], v[180:183], v[244:247], 0
	v_mfma_f32_16x16x32_bf16 v[66:69], v[188:191], v[244:247], 0
	v_mfma_f32_16x16x32_bf16 v[122:125], v[184:187], v[200:203], v[122:125]
	v_mfma_f32_16x16x32_bf16 v[114:117], v[192:195], v[200:203], v[114:117]
	v_mfma_f32_16x16x32_bf16 v[106:109], v[184:187], v[220:223], v[106:109]
	v_mfma_f32_16x16x32_bf16 v[98:101], v[192:195], v[220:223], v[98:101]
	v_mfma_f32_16x16x32_bf16 v[90:93], v[184:187], v[240:243], v[90:93]
	v_mfma_f32_16x16x32_bf16 v[82:85], v[192:195], v[240:243], v[82:85]
	v_mfma_f32_16x16x32_bf16 v[74:77], v[184:187], v[248:251], v[74:77]
	v_mfma_f32_16x16x32_bf16 v[66:69], v[192:195], v[248:251], v[66:69]
	s_barrier
	s_add_i32 s57, s57, s44
	v_lshl_add_u64 v[146:147], s[34:35], 0, v[134:135]
	s_mov_b32 m0, s57
	ds_read_b128 v[196:199], v157 offset:16384
	ds_read_b128 v[200:203], v157 offset:17408
	ds_read_b128 v[204:207], v157 offset:18432
	ds_read_b128 v[220:223], v157 offset:19456
	ds_read_b128 v[236:239], v157 offset:20480
	ds_read_b128 v[240:243], v157 offset:21504
	ds_read_b128 v[244:247], v157 offset:22528
	ds_read_b128 v[248:251], v157 offset:23552
	global_load_lds_dwordx4 v[146:147], off
	s_add_i32 m0, s57, 0x2000
	s_add_u32 s58, s34, 0x40000
	v_lshl_add_u64 v[208:209], s[34:35], 0, v[130:131]
	s_addc_u32 s59, s35, 0
	s_add_i32 s57, s60, s44
	global_load_lds_dwordx4 v[208:209], off
	v_lshl_add_u64 v[224:225], s[58:59], 0, v[134:135]
	s_mov_b32 m0, s57
	v_lshl_add_u64 v[230:231], s[36:37], 0, v[132:133]
	global_load_lds_dwordx4 v[224:225], off
	v_lshl_add_u64 v[224:225], s[58:59], 0, v[130:131]
	s_add_i32 m0, s57, 0x2000
	s_nop 0
	global_load_lds_dwordx4 v[224:225], off
	v_lshl_add_u64 v[224:225], s[36:37], 0, v[136:137]
	s_mov_b32 m0, s48
	s_nop 0
	global_load_lds_dwordx4 v[224:225], off
	s_mov_b32 m0, s49
	s_nop 0
	global_load_lds_dwordx4 v[230:231], off
	s_nop 0
	s_nop 0
	s_nop 0
	s_waitcnt vmcnt(8)
	s_waitcnt lgkmcnt(0)
	s_barrier
	s_waitcnt lgkmcnt(0)
	v_mfma_f32_16x16x32_bf16 v[62:65], v[142:145], v[196:199], 0
	v_mfma_f32_16x16x32_bf16 v[54:57], v[172:175], v[196:199], 0
	v_mfma_f32_16x16x32_bf16 v[46:49], v[142:145], v[204:207], 0
	v_mfma_f32_16x16x32_bf16 v[38:41], v[172:175], v[204:207], 0
	v_mfma_f32_16x16x32_bf16 v[30:33], v[142:145], v[236:239], 0
	v_mfma_f32_16x16x32_bf16 v[22:25], v[172:175], v[236:239], 0
	v_mfma_f32_16x16x32_bf16 v[14:17], v[142:145], v[244:247], 0
	v_mfma_f32_16x16x32_bf16 v[6:9], v[172:175], v[244:247], 0
	v_mfma_f32_16x16x32_bf16 v[62:65], v[168:171], v[200:203], v[62:65]
	v_mfma_f32_16x16x32_bf16 v[54:57], v[176:179], v[200:203], v[54:57]
	v_mfma_f32_16x16x32_bf16 v[46:49], v[168:171], v[220:223], v[46:49]
	v_mfma_f32_16x16x32_bf16 v[38:41], v[176:179], v[220:223], v[38:41]
	v_mfma_f32_16x16x32_bf16 v[30:33], v[168:171], v[240:243], v[30:33]
	v_mfma_f32_16x16x32_bf16 v[22:25], v[176:179], v[240:243], v[22:25]
	v_mfma_f32_16x16x32_bf16 v[14:17], v[168:171], v[248:251], v[14:17]
	v_mfma_f32_16x16x32_bf16 v[6:9], v[176:179], v[248:251], v[6:9]
	v_mfma_f32_16x16x32_bf16 v[58:61], v[180:183], v[196:199], 0
	v_mfma_f32_16x16x32_bf16 v[50:53], v[188:191], v[196:199], 0
	v_mfma_f32_16x16x32_bf16 v[42:45], v[180:183], v[204:207], 0
	v_mfma_f32_16x16x32_bf16 v[34:37], v[188:191], v[204:207], 0
	v_mfma_f32_16x16x32_bf16 v[26:29], v[180:183], v[236:239], 0
	v_mfma_f32_16x16x32_bf16 v[18:21], v[188:191], v[236:239], 0
	v_mfma_f32_16x16x32_bf16 v[10:13], v[180:183], v[244:247], 0
	v_mfma_f32_16x16x32_bf16 v[2:5], v[188:191], v[244:247], 0
	v_mfma_f32_16x16x32_bf16 v[58:61], v[184:187], v[200:203], v[58:61]
	v_mfma_f32_16x16x32_bf16 v[50:53], v[192:195], v[200:203], v[50:53]
	v_mfma_f32_16x16x32_bf16 v[42:45], v[184:187], v[220:223], v[42:45]
	v_mfma_f32_16x16x32_bf16 v[34:37], v[192:195], v[220:223], v[34:37]
	v_mfma_f32_16x16x32_bf16 v[26:29], v[184:187], v[240:243], v[26:29]
	v_mfma_f32_16x16x32_bf16 v[18:21], v[192:195], v[240:243], v[18:21]
	v_mfma_f32_16x16x32_bf16 v[10:13], v[184:187], v[248:251], v[10:13]
	v_mfma_f32_16x16x32_bf16 v[2:5], v[192:195], v[248:251], v[2:5]
	s_barrier
	s_add_i32 s57, 0, 0x18000
	v_add_u32_e32 v164, s57, v155
	s_add_i32 s58, 0, 0x1c000
	ds_read_b128 v[142:145], v164
	ds_read_b128 v[168:171], v164 offset:1024
	ds_read_b128 v[172:175], v164 offset:2048
	ds_read_b128 v[176:179], v164 offset:3072
	v_add_u32_e32 v164, s58, v155
	ds_read_b128 v[180:183], v164
	ds_read_b128 v[184:187], v164 offset:1024
	ds_read_b128 v[188:191], v164 offset:2048
	ds_read_b128 v[192:195], v164 offset:3072
	s_add_u32 s36, s36, 0x40000
	s_addc_u32 s37, s37, 0
	s_mov_b32 m0, s50
	v_lshl_add_u64 v[252:253], s[36:37], 0, v[136:137]
	ds_read_b128 v[196:199], v157 offset:32768
	ds_read_b128 v[200:203], v157 offset:33792
	ds_read_b128 v[204:207], v157 offset:34816
	ds_read_b128 v[220:223], v157 offset:35840
	ds_read_b128 v[236:239], v157 offset:36864
	ds_read_b128 v[240:243], v157 offset:37888
	ds_read_b128 v[244:247], v157 offset:38912
	ds_read_b128 v[248:251], v157 offset:39936
	global_load_lds_dwordx4 v[252:253], off
	v_lshl_add_u64 v[252:253], s[36:37], 0, v[132:133]
	s_mov_b32 m0, s51
	s_nop 0
	global_load_lds_dwordx4 v[252:253], off
	s_nop 0
	s_nop 0
	s_nop 0
	s_nop 0
	s_nop 0
	s_nop 0
	s_nop 0
	s_waitcnt vmcnt(8)
	s_waitcnt lgkmcnt(0)
	s_barrier
	s_waitcnt lgkmcnt(0)
	v_mfma_f32_16x16x32_bf16 v[126:129], v[142:145], v[196:199], v[126:129]
	v_mfma_f32_16x16x32_bf16 v[118:121], v[172:175], v[196:199], v[118:121]
	v_mfma_f32_16x16x32_bf16 v[110:113], v[142:145], v[204:207], v[110:113]
	v_mfma_f32_16x16x32_bf16 v[102:105], v[172:175], v[204:207], v[102:105]
	v_mfma_f32_16x16x32_bf16 v[94:97], v[142:145], v[236:239], v[94:97]
	v_mfma_f32_16x16x32_bf16 v[86:89], v[172:175], v[236:239], v[86:89]
	v_mfma_f32_16x16x32_bf16 v[78:81], v[142:145], v[244:247], v[78:81]
	v_mfma_f32_16x16x32_bf16 v[70:73], v[172:175], v[244:247], v[70:73]
	v_mfma_f32_16x16x32_bf16 v[126:129], v[168:171], v[200:203], v[126:129]
	v_mfma_f32_16x16x32_bf16 v[118:121], v[176:179], v[200:203], v[118:121]
	v_mfma_f32_16x16x32_bf16 v[110:113], v[168:171], v[220:223], v[110:113]
	v_mfma_f32_16x16x32_bf16 v[102:105], v[176:179], v[220:223], v[102:105]
	v_mfma_f32_16x16x32_bf16 v[94:97], v[168:171], v[240:243], v[94:97]
	v_mfma_f32_16x16x32_bf16 v[86:89], v[176:179], v[240:243], v[86:89]
	v_mfma_f32_16x16x32_bf16 v[78:81], v[168:171], v[248:251], v[78:81]
	v_mfma_f32_16x16x32_bf16 v[70:73], v[176:179], v[248:251], v[70:73]
	v_mfma_f32_16x16x32_bf16 v[122:125], v[180:183], v[196:199], v[122:125]
	v_mfma_f32_16x16x32_bf16 v[114:117], v[188:191], v[196:199], v[114:117]
	v_mfma_f32_16x16x32_bf16 v[106:109], v[180:183], v[204:207], v[106:109]
	v_mfma_f32_16x16x32_bf16 v[98:101], v[188:191], v[204:207], v[98:101]
	v_mfma_f32_16x16x32_bf16 v[90:93], v[180:183], v[236:239], v[90:93]
	v_mfma_f32_16x16x32_bf16 v[82:85], v[188:191], v[236:239], v[82:85]
	v_mfma_f32_16x16x32_bf16 v[74:77], v[180:183], v[244:247], v[74:77]
	v_mfma_f32_16x16x32_bf16 v[66:69], v[188:191], v[244:247], v[66:69]
	v_mfma_f32_16x16x32_bf16 v[122:125], v[184:187], v[200:203], v[122:125]
	v_mfma_f32_16x16x32_bf16 v[114:117], v[192:195], v[200:203], v[114:117]
	v_mfma_f32_16x16x32_bf16 v[106:109], v[184:187], v[220:223], v[106:109]
	v_mfma_f32_16x16x32_bf16 v[98:101], v[192:195], v[220:223], v[98:101]
	v_mfma_f32_16x16x32_bf16 v[90:93], v[184:187], v[240:243], v[90:93]
	v_mfma_f32_16x16x32_bf16 v[82:85], v[192:195], v[240:243], v[82:85]
	v_mfma_f32_16x16x32_bf16 v[74:77], v[184:187], v[248:251], v[74:77]
	v_mfma_f32_16x16x32_bf16 v[66:69], v[192:195], v[248:251], v[66:69]
	s_barrier
	s_add_i32 s36, s57, s44
	v_lshl_add_u64 v[146:147], v[146:147], 0, s[96:97]
	s_mov_b32 m0, s36
	ds_read_b128 v[196:199], v157 offset:49152
	ds_read_b128 v[200:203], v157 offset:50176
	ds_read_b128 v[204:207], v157 offset:51200
	ds_read_b128 v[220:223], v157 offset:52224
	ds_read_b128 v[236:239], v157 offset:53248
	ds_read_b128 v[240:243], v157 offset:54272
	ds_read_b128 v[244:247], v157 offset:55296
	ds_read_b128 v[248:251], v157 offset:56320
	global_load_lds_dwordx4 v[146:147], off
	s_add_i32 m0, s36, 0x2000
	s_add_u32 s34, s34, 0x40080
	v_lshl_add_u64 v[146:147], v[208:209], 0, s[96:97]
	s_addc_u32 s35, s35, 0
	s_add_i32 s36, s58, s44
	global_load_lds_dwordx4 v[146:147], off
	v_lshl_add_u64 v[146:147], s[34:35], 0, v[134:135]
	s_mov_b32 m0, s36
	s_nop 0
	global_load_lds_dwordx4 v[146:147], off
	v_lshl_add_u64 v[146:147], s[34:35], 0, v[130:131]
	s_add_i32 m0, s36, 0x2000
	s_nop 0
	global_load_lds_dwordx4 v[146:147], off
	v_lshl_add_u64 v[146:147], v[224:225], 0, s[96:97]
	s_mov_b32 m0, s52
	s_nop 0
	global_load_lds_dwordx4 v[146:147], off
	v_lshl_add_u64 v[146:147], v[230:231], 0, s[96:97]
	s_mov_b32 m0, s53
	s_nop 0
	global_load_lds_dwordx4 v[146:147], off
	s_nop 0
	s_nop 0
	s_waitcnt vmcnt(8)
	s_waitcnt lgkmcnt(0)
	s_barrier
	s_waitcnt lgkmcnt(0)
	v_mfma_f32_16x16x32_bf16 v[62:65], v[142:145], v[196:199], v[62:65]
	v_mfma_f32_16x16x32_bf16 v[54:57], v[172:175], v[196:199], v[54:57]
	v_mfma_f32_16x16x32_bf16 v[46:49], v[142:145], v[204:207], v[46:49]
	v_mfma_f32_16x16x32_bf16 v[38:41], v[172:175], v[204:207], v[38:41]
	v_mfma_f32_16x16x32_bf16 v[30:33], v[142:145], v[236:239], v[30:33]
	v_mfma_f32_16x16x32_bf16 v[22:25], v[172:175], v[236:239], v[22:25]
	v_mfma_f32_16x16x32_bf16 v[14:17], v[142:145], v[244:247], v[14:17]
	v_mfma_f32_16x16x32_bf16 v[6:9], v[172:175], v[244:247], v[6:9]
	v_mfma_f32_16x16x32_bf16 v[62:65], v[168:171], v[200:203], v[62:65]
	v_mfma_f32_16x16x32_bf16 v[54:57], v[176:179], v[200:203], v[54:57]
	v_mfma_f32_16x16x32_bf16 v[46:49], v[168:171], v[220:223], v[46:49]
	v_mfma_f32_16x16x32_bf16 v[38:41], v[176:179], v[220:223], v[38:41]
	v_mfma_f32_16x16x32_bf16 v[30:33], v[168:171], v[240:243], v[30:33]
	v_mfma_f32_16x16x32_bf16 v[22:25], v[176:179], v[240:243], v[22:25]
	v_mfma_f32_16x16x32_bf16 v[14:17], v[168:171], v[248:251], v[14:17]
	v_mfma_f32_16x16x32_bf16 v[6:9], v[176:179], v[248:251], v[6:9]
	v_mfma_f32_16x16x32_bf16 v[58:61], v[180:183], v[196:199], v[58:61]
	v_mfma_f32_16x16x32_bf16 v[50:53], v[188:191], v[196:199], v[50:53]
	v_mfma_f32_16x16x32_bf16 v[42:45], v[180:183], v[204:207], v[42:45]
	v_mfma_f32_16x16x32_bf16 v[34:37], v[188:191], v[204:207], v[34:37]
	v_mfma_f32_16x16x32_bf16 v[26:29], v[180:183], v[236:239], v[26:29]
	v_mfma_f32_16x16x32_bf16 v[18:21], v[188:191], v[236:239], v[18:21]
	v_mfma_f32_16x16x32_bf16 v[10:13], v[180:183], v[244:247], v[10:13]
	v_mfma_f32_16x16x32_bf16 v[2:5], v[188:191], v[244:247], v[2:5]
	v_mfma_f32_16x16x32_bf16 v[58:61], v[184:187], v[200:203], v[58:61]
	v_mfma_f32_16x16x32_bf16 v[50:53], v[192:195], v[200:203], v[50:53]
	v_mfma_f32_16x16x32_bf16 v[42:45], v[184:187], v[220:223], v[42:45]
	v_mfma_f32_16x16x32_bf16 v[34:37], v[192:195], v[220:223], v[34:37]
	v_mfma_f32_16x16x32_bf16 v[26:29], v[184:187], v[240:243], v[26:29]
	v_mfma_f32_16x16x32_bf16 v[18:21], v[192:195], v[240:243], v[18:21]
	v_mfma_f32_16x16x32_bf16 v[10:13], v[184:187], v[248:251], v[10:13]
	v_mfma_f32_16x16x32_bf16 v[2:5], v[192:195], v[248:251], v[2:5]
	s_barrier
	s_add_i32 s56, s56, 2
	s_add_u32 s41, s41, 0x100
	s_addc_u32 s43, s43, 0
	s_add_u32 s30, s30, 0x100
	s_addc_u32 s31, s31, 0
	s_cmp_gt_u32 s56, 13
